# opt6
# speedup vs baseline: 1.0091x; 1.0091x over previous
; __device__ __forceinline__ int opaque_tid() { int t = threadIdx.x; asm volatile("" : "+v"(t)); return t; }
; #define WAIT_V(n) asm volatile("s_waitcnt vmcnt(" #n ")" ::: "memory")
; #define BAR __builtin_amdgcn_s_barrier()
; template <bool PEEL = false>
; __device__ __forceinline__ void gemm_tile(f32x4 (&acc)[2][2][4][2], const u16* __restrict__ A, int lda,
;                                           const u16* __restrict__ B, int K) {
;     ...
;   const int tid = opaque_tid();
;   const int wid = tid >> 6, lane = tid & 63, wr = wid >> 2, wc = wid & 3, fr = lane & 15, fq = lane >> 4;
;   int rA0, rB0;
;   {
;     int r, c;
;     stage_rc(tid * 16, r, c);
;     rA0 = (r * lda + c) * 2; rB0 = (r * K + c) * 2;
;   }
;   const int wbase = __builtin_amdgcn_readfirstlane(wid) * 1024;
;   const __amdgpu_buffer_rsrc_t rsA = __builtin_amdgcn_make_buffer_rsrc((void*)A, 0, 0x40000000, 0x00020000);
;   const __amdgpu_buffer_rsrc_t rsB = __builtin_amdgcn_make_buffer_rsrc((void*)B, 0, 0x40000000, 0x00020000);
; #pragma unroll
;   for (int a = 0; a < 2; ++a)
; #pragma unroll
;     for (int b = 0; b < 2; ++b)
; #pragma unroll
;       for (int m = 0; m < 4; ++m)
; #pragma unroll
;         for (int n = 0; n < 2; ++n) acc[a][b][m][n] = f32x4{0.f, 0.f, 0.f, 0.f};
;   bf16x8 At[4][2], B0[2][2], B1[2][2];
;   const int nt = K / 64;
;   STAGE_B(SB(0, 0), 0, 0); STAGE_A(SA(0, 0), 0, 0);
;   STAGE_B(SB(0, 1), 1, 0); STAGE_A(SA(0, 1), 1, 0);
;   if (wr == 1) BAR;
;   WAIT_V(4); BAR;
;   STAGE_B(SB(1, 0), 0, 1); STAGE_A(SA(1, 0), 0, 1); STAGE_B(SB(1, 1), 1, 1);
;   WAIT_V(6); BAR;
.LBB0_262:
	v_mov_b32_e32 v128, v254
	s_lshl_b32 s4, s21, 19
	v_bfe_i32 v3, v128, 27, 1
	v_lshlrev_b32_e32 v1, 4, v128
	v_lshrrev_b32_e32 v3, 22, v3
	v_add_u32_e32 v3, v1, v3
	v_and_b32_e32 v3, 0xfffffc00, v3
	v_sub_u32_e32 v1, v1, v3
	v_lshrrev_b32_e32 v3, 4, v1
	v_bitop3_b32 v3, v3, v1, 32 bitop3:0x6c
	v_ashrrev_i32_e32 v1, 31, v1
	v_ashrrev_i32_e32 v2, 31, v128
	v_lshrrev_b32_e32 v1, 26, v1
	v_lshrrev_b32_e32 v2, 26, v2
	v_add_u32_e32 v1, v3, v1
	v_ashrrev_i32_e32 v0, 6, v128
	v_add_u32_e32 v2, v128, v2
	v_ashrrev_i32_e32 v1, 6, v1
	s_add_u32 s4, s1, s4
	v_ashrrev_i32_e32 v2, 6, v2
	v_mul_i32_i24_e32 v5, 64, v1
	v_readfirstlane_b32 s14, v0
	s_addc_u32 s5, s20, 0
	v_lshlrev_b32_e32 v4, 3, v2
	v_lshlrev_b32_e32 v2, 5, v2
	v_sub_u32_e32 v3, v3, v5
	s_lshl_b32 s78, s14, 10
	v_and_b32_e32 v4, 0x1ffff0, v4
	v_and_b32_e32 v2, 32, v2
	v_ashrrev_i16_sdwa v3, v142, sext(v3) dst_sel:DWORD dst_unused:UNUSED_PAD src0_sel:DWORD src1_sel:BYTE_0
	s_add_i32 s16, s78, 0
	v_add_u32_sdwa v2, v2, sext(v3) dst_sel:DWORD dst_unused:UNUSED_PAD src0_sel:DWORD src1_sel:WORD_0
	v_add_lshl_u32 v1, v1, v4, 11
	s_add_i32 s17, s16, 0x10000
	v_lshl_add_u32 v133, v2, 1, v1
	s_and_b32 s5, s5, 0xffff
	s_add_i32 s40, s16, 0x12000
	s_add_i32 s41, s16, 0x2000
	s_add_i32 s42, s16, 0x14000
	s_add_i32 s43, s16, 0x16000
	s_add_i32 s45, s16, 0x4000
	s_add_i32 s46, s16, 0x6000
	s_add_i32 s47, s16, 0x8000
	s_add_i32 s67, s16, 0xa000
	s_add_i32 s78, s68, s16
	s_add_i32 s79, s78, 0x2000
	v_ashrrev_i32_e32 v1, 8, v128
	v_cmp_eq_u32_e32 vcc, 1, v1
	s_cmp_lg_u32 s21, 0
	s_cbranch_scc1 .Lpf3_hdr
	s_mov_b32 m0, s17
	s_nop 0
	buffer_load_dwordx4 v133, s[4:7], 0 offen lds
	s_mov_b32 m0, s40
	s_nop 0
	buffer_load_dwordx4 v133, s[4:7], s7 offen lds
	s_mov_b32 m0, s16
	s_nop 0
	buffer_load_dwordx4 v133, s[56:59], 0 offen lds
	s_mov_b32 m0, s41
	s_nop 0
	buffer_load_dwordx4 v133, s[56:59], s7 offen lds
	s_mov_b32 m0, s42
	s_nop 0
	buffer_load_dwordx4 v133, s[4:7], s22 offen lds
	s_mov_b32 m0, s43
	s_nop 0
	buffer_load_dwordx4 v133, s[4:7], s23 offen lds
	s_mov_b32 m0, s45
	s_nop 0
	buffer_load_dwordx4 v133, s[56:59], s22 offen lds
	s_mov_b32 m0, s46
	s_nop 0
	buffer_load_dwordx4 v133, s[56:59], s23 offen lds
	s_and_saveexec_b64 s[14:15], vcc
	s_cbranch_execz .Lpf3_b0
	s_barrier
.Lpf3_b0:
	s_or_b64 exec, exec, s[14:15]
	s_waitcnt vmcnt(4)
	s_barrier
	s_add_i32 m0, s16, 0x18000
	s_nop 0
	buffer_load_dwordx4 v133, s[4:7], s24 offen lds
	s_add_i32 m0, s16, 0x1a000
	s_nop 0
	buffer_load_dwordx4 v133, s[4:7], s25 offen lds
	s_mov_b32 m0, s47
	s_nop 0
	buffer_load_dwordx4 v133, s[56:59], s24 offen lds
	s_mov_b32 m0, s67
	s_nop 0
	buffer_load_dwordx4 v133, s[56:59], s25 offen lds
	s_mov_b32 m0, s78
	s_nop 0
	buffer_load_dwordx4 v133, s[4:7], s26 offen lds
	s_mov_b32 m0, s79
	s_nop 0
	buffer_load_dwordx4 v133, s[4:7], s27 offen lds
	s_waitcnt vmcnt(6)
	s_branch .Lpf3_join
.Lpf3_hdr:
	s_and_saveexec_b64 s[14:15], vcc
	s_cbranch_execz .Lpf3_b1
	s_barrier
.Lpf3_b1:
	s_or_b64 exec, exec, s[14:15]
	s_waitcnt vmcnt(42)
	s_barrier
	s_waitcnt vmcnt(38)
.Lpf3_join:
	s_add_i32 s14, s16, 0x18000
	s_add_i32 s15, s16, 0x1a000
	v_and_b32_e32 v2, 15, v128
	v_lshlrev_b32_e32 v0, 12, v0
	v_and_b32_e32 v126, 0x3000, v0
	v_lshlrev_b32_e32 v0, 6, v2
	v_lshlrev_b32_e32 v2, 2, v128
	v_and_b32_e32 v26, 48, v128
	v_and_b32_e32 v27, 32, v2
	v_bitop3_b32 v127, v0, v27, v26 bitop3:0x36
	v_add_u32_e32 v0, s69, v127
	v_add_u32_e32 v134, v0, v126
	s_barrier
	ds_read_b128 v[2:5], v134
	ds_read_b128 v[6:9], v134 offset:1024
	ds_read_b128 v[10:13], v134 offset:2048
	ds_read_b128 v[14:17], v134 offset:3072
	v_lshlrev_b32_e32 v0, 13, v1
	v_add_u32_e32 v1, 0, v127
	v_add_u32_e32 v129, v1, v0
	v_lshlrev_b32_e32 v1, 6, v128
	s_movk_i32 s82, 0x3c0
	v_and_or_b32 v1, v1, s82, v26
	v_xad_u32 v1, v1, v27, 0
	v_or_b32_e32 v26, 0x800, v0
	v_or_b32_e32 v34, 0x1000, v0
	v_or_b32_e32 v0, 0x1800, v0
	s_add_i32 s82, s16, 0xc000
	v_add_u32_e32 v130, v1, v26
	v_add_u32_e32 v131, v1, v34
	v_add_u32_e32 v132, v1, v0
	s_mov_b32 m0, s82
	s_add_i32 s83, s16, 0xe000
	ds_read_b128 v[18:21], v129
	ds_read_b128 v[22:25], v129 offset:1024
	ds_read_b128 v[26:29], v130
	ds_read_b128 v[30:33], v130 offset:1024
	ds_read_b128 v[34:37], v131
	ds_read_b128 v[38:41], v131 offset:1024
	ds_read_b128 v[42:45], v132
	ds_read_b128 v[46:49], v132 offset:1024
	buffer_load_dwordx4 v133, s[56:59], s26 offen lds
	s_mov_b32 m0, s83
	s_nop 0
	buffer_load_dwordx4 v133, s[56:59], s27 offen lds
	s_waitcnt lgkmcnt(8)
	s_barrier
	s_waitcnt lgkmcnt(0)
	s_setprio 1
	s_waitcnt lgkmcnt(7)
	v_mfma_f32_16x16x32_bf16 v[50:53], v[18:21], v[2:5], 0
	v_mfma_f32_16x16x32_bf16 v[54:57], v[18:21], v[10:13], 0
	s_waitcnt lgkmcnt(5)
	v_mfma_f32_16x16x32_bf16 v[58:61], v[26:29], v[2:5], 0
	v_mfma_f32_16x16x32_bf16 v[62:65], v[26:29], v[10:13], 0
	s_waitcnt lgkmcnt(3)
	v_mfma_f32_16x16x32_bf16 v[66:69], v[34:37], v[2:5], 0
	v_mfma_f32_16x16x32_bf16 v[70:73], v[34:37], v[10:13], 0
	s_waitcnt lgkmcnt(1)
	v_mfma_f32_16x16x32_bf16 v[74:77], v[42:45], v[2:5], 0
	v_mfma_f32_16x16x32_bf16 v[78:81], v[42:45], v[10:13], 0
	v_mfma_f32_16x16x32_bf16 v[50:53], v[22:25], v[6:9], v[50:53]
	v_mfma_f32_16x16x32_bf16 v[54:57], v[22:25], v[14:17], v[54:57]
	v_mfma_f32_16x16x32_bf16 v[58:61], v[30:33], v[6:9], v[58:61]
	v_mfma_f32_16x16x32_bf16 v[62:65], v[30:33], v[14:17], v[62:65]
	v_mfma_f32_16x16x32_bf16 v[66:69], v[38:41], v[6:9], v[66:69]
	v_mfma_f32_16x16x32_bf16 v[70:73], v[38:41], v[14:17], v[70:73]
	s_waitcnt lgkmcnt(0)
	v_mfma_f32_16x16x32_bf16 v[74:77], v[46:49], v[6:9], v[74:77]
	v_mfma_f32_16x16x32_bf16 v[78:81], v[46:49], v[14:17], v[78:81]
	s_setprio 0
	s_barrier
	v_add_u32_e32 v0, s70, v127
	v_add_u32_e32 v135, v0, v126
	s_mov_b32 m0, s17
	ds_read_b128 v[82:85], v135
	ds_read_b128 v[86:89], v135 offset:1024
	ds_read_b128 v[90:93], v135 offset:2048
	ds_read_b128 v[94:97], v135 offset:3072
	buffer_load_dwordx4 v133, s[4:7], s0 offen lds
	s_mov_b32 m0, s40
	s_nop 0
	buffer_load_dwordx4 v133, s[4:7], s28 offen lds
	s_barrier
	s_waitcnt lgkmcnt(0)
	s_setprio 1
	s_waitcnt lgkmcnt(3)
	v_mfma_f32_16x16x32_bf16 v[98:101], v[18:21], v[82:85], 0
	s_waitcnt lgkmcnt(1)
	v_mfma_f32_16x16x32_bf16 v[18:21], v[18:21], v[90:93], 0
	s_waitcnt lgkmcnt(0)
	v_mfma_f32_16x16x32_bf16 v[102:105], v[22:25], v[94:97], v[18:21]
	v_mfma_f32_16x16x32_bf16 v[18:21], v[26:29], v[82:85], 0
	v_mfma_f32_16x16x32_bf16 v[106:109], v[30:33], v[86:89], v[18:21]
	v_mfma_f32_16x16x32_bf16 v[18:21], v[26:29], v[90:93], 0
	v_mfma_f32_16x16x32_bf16 v[110:113], v[30:33], v[94:97], v[18:21]
	v_mfma_f32_16x16x32_bf16 v[18:21], v[34:37], v[82:85], 0
	v_mfma_f32_16x16x32_bf16 v[114:117], v[38:41], v[86:89], v[18:21]
	v_mfma_f32_16x16x32_bf16 v[18:21], v[34:37], v[90:93], 0
	v_mfma_f32_16x16x32_bf16 v[32:35], v[38:41], v[94:97], v[18:21]
	v_mfma_f32_16x16x32_bf16 v[18:21], v[42:45], v[82:85], 0
	v_mfma_f32_16x16x32_bf16 v[36:39], v[46:49], v[86:89], v[18:21]
	v_mfma_f32_16x16x32_bf16 v[18:21], v[42:45], v[90:93], 0
	v_mfma_f32_16x16x32_bf16 v[98:101], v[22:25], v[86:89], v[98:101]
	v_mfma_f32_16x16x32_bf16 v[118:121], v[46:49], v[94:97], v[18:21]
	s_setprio 0
	s_mov_b32 m0, s16
	s_barrier
	s_nop 2
	ds_read_b128 v[18:21], v129 offset:16384
	ds_read_b128 v[22:25], v129 offset:17408
	ds_read_b128 v[26:29], v130 offset:16384
	ds_read_b128 v[40:43], v130 offset:17408
	ds_read_b128 v[44:47], v131 offset:16384
	ds_read_b128 v[122:125], v131 offset:17408
	ds_read_b128 v[144:147], v132 offset:16384
	ds_read_b128 v[148:151], v132 offset:17408
	buffer_load_dwordx4 v133, s[56:59], s0 offen lds
	s_mov_b32 m0, s41
	s_nop 0
	buffer_load_dwordx4 v133, s[56:59], s28 offen lds
	s_barrier
	s_waitcnt lgkmcnt(0)
	s_setprio 1
	s_waitcnt lgkmcnt(7)
	v_mfma_f32_16x16x32_bf16 v[152:155], v[18:21], v[2:5], 0
	s_waitcnt lgkmcnt(5)
	v_mfma_f32_16x16x32_bf16 v[160:163], v[26:29], v[2:5], 0
	s_waitcnt lgkmcnt(3)
	v_mfma_f32_16x16x32_bf16 v[168:171], v[44:47], v[2:5], 0
	s_waitcnt lgkmcnt(1)
	v_mfma_f32_16x16x32_bf16 v[0:3], v[144:147], v[2:5], 0
	v_mfma_f32_16x16x32_bf16 v[156:159], v[18:21], v[10:13], 0
	v_mfma_f32_16x16x32_bf16 v[164:167], v[26:29], v[10:13], 0
	v_mfma_f32_16x16x32_bf16 v[172:175], v[44:47], v[10:13], 0
	s_waitcnt lgkmcnt(0)
	v_mfma_f32_16x16x32_bf16 v[176:179], v[148:151], v[6:9], v[0:3]
	v_mfma_f32_16x16x32_bf16 v[0:3], v[144:147], v[10:13], 0
	v_mfma_f32_16x16x32_bf16 v[152:155], v[22:25], v[6:9], v[152:155]
	v_mfma_f32_16x16x32_bf16 v[156:159], v[22:25], v[14:17], v[156:159]
	v_mfma_f32_16x16x32_bf16 v[160:163], v[40:43], v[6:9], v[160:163]
	v_mfma_f32_16x16x32_bf16 v[164:167], v[40:43], v[14:17], v[164:167]
	v_mfma_f32_16x16x32_bf16 v[168:171], v[122:125], v[6:9], v[168:171]
	v_mfma_f32_16x16x32_bf16 v[172:175], v[122:125], v[14:17], v[172:175]
	v_mfma_f32_16x16x32_bf16 v[180:183], v[148:151], v[14:17], v[0:3]
	s_setprio 0
	s_barrier
	s_mov_b32 m0, s42
	s_nop 0
	buffer_load_dwordx4 v133, s[4:7], s29 offen lds
	s_mov_b32 m0, s43
	s_nop 0
	buffer_load_dwordx4 v133, s[4:7], s34 offen lds
	s_waitcnt vmcnt(6)
	s_barrier
	s_setprio 1
	v_mfma_f32_16x16x32_bf16 v[0:3], v[18:21], v[82:85], 0
	v_mfma_f32_16x16x32_bf16 v[184:187], v[22:25], v[86:89], v[0:3]
	v_mfma_f32_16x16x32_bf16 v[0:3], v[18:21], v[90:93], 0
	v_mfma_f32_16x16x32_bf16 v[188:191], v[22:25], v[94:97], v[0:3]
	v_mfma_f32_16x16x32_bf16 v[0:3], v[26:29], v[82:85], 0
	v_mfma_f32_16x16x32_bf16 v[192:195], v[40:43], v[86:89], v[0:3]
	v_mfma_f32_16x16x32_bf16 v[0:3], v[26:29], v[90:93], 0
	v_mfma_f32_16x16x32_bf16 v[196:199], v[40:43], v[94:97], v[0:3]
	v_mfma_f32_16x16x32_bf16 v[0:3], v[44:47], v[82:85], 0
	v_mfma_f32_16x16x32_bf16 v[200:203], v[122:125], v[86:89], v[0:3]
	v_mfma_f32_16x16x32_bf16 v[0:3], v[44:47], v[90:93], 0
	v_mfma_f32_16x16x32_bf16 v[204:207], v[122:125], v[94:97], v[0:3]
	v_mfma_f32_16x16x32_bf16 v[0:3], v[144:147], v[82:85], 0
	v_mfma_f32_16x16x32_bf16 v[208:211], v[148:151], v[86:89], v[0:3]
	v_mfma_f32_16x16x32_bf16 v[0:3], v[144:147], v[90:93], 0
	v_mfma_f32_16x16x32_bf16 v[144:147], v[148:151], v[94:97], v[0:3]
	s_setprio 0
	s_nop 5
	v_add_u32_e32 v0, s97, v127
	v_add_u32_e32 v136, v0, v126
	s_barrier
	ds_read_b128 v[122:125], v136
	ds_read_b128 v[148:151], v136 offset:1024
	ds_read_b128 v[212:215], v136 offset:2048
	ds_read_b128 v[216:219], v136 offset:3072
	s_mov_b32 m0, s45
	ds_read_b128 v[40:43], v129 offset:32768
	ds_read_b128 v[44:47], v129 offset:33792
	ds_read_b128 v[82:85], v130 offset:32768
	ds_read_b128 v[86:89], v130 offset:33792
	ds_read_b128 v[90:93], v131 offset:32768
	ds_read_b128 v[94:97], v131 offset:33792
	ds_read_b128 v[220:223], v132 offset:32768
	ds_read_b128 v[224:227], v132 offset:33792
	buffer_load_dwordx4 v133, s[56:59], s29 offen lds
	s_mov_b32 m0, s46
	s_nop 0
	buffer_load_dwordx4 v133, s[56:59], s34 offen lds
	s_waitcnt lgkmcnt(8)
	s_barrier
	s_waitcnt lgkmcnt(0)
	s_setprio 1
	s_waitcnt lgkmcnt(7)
	v_mfma_f32_16x16x32_bf16 v[0:3], v[40:43], v[122:125], v[50:53]
	s_waitcnt lgkmcnt(6)
	v_mfma_f32_16x16x32_bf16 v[28:31], v[44:47], v[148:151], v[0:3]
	v_mfma_f32_16x16x32_bf16 v[0:3], v[40:43], v[212:215], v[54:57]
	v_mfma_f32_16x16x32_bf16 v[24:27], v[44:47], v[216:219], v[0:3]
	s_waitcnt lgkmcnt(5)
	v_mfma_f32_16x16x32_bf16 v[0:3], v[82:85], v[122:125], v[58:61]
	s_waitcnt lgkmcnt(4)
	v_mfma_f32_16x16x32_bf16 v[20:23], v[86:89], v[148:151], v[0:3]
	v_mfma_f32_16x16x32_bf16 v[0:3], v[82:85], v[212:215], v[62:65]
	v_mfma_f32_16x16x32_bf16 v[16:19], v[86:89], v[216:219], v[0:3]
	s_waitcnt lgkmcnt(3)
	v_mfma_f32_16x16x32_bf16 v[0:3], v[90:93], v[122:125], v[66:69]
	s_waitcnt lgkmcnt(2)
	v_mfma_f32_16x16x32_bf16 v[12:15], v[94:97], v[148:151], v[0:3]
	v_mfma_f32_16x16x32_bf16 v[0:3], v[90:93], v[212:215], v[70:73]
	v_mfma_f32_16x16x32_bf16 v[8:11], v[94:97], v[216:219], v[0:3]
	s_waitcnt lgkmcnt(1)
	v_mfma_f32_16x16x32_bf16 v[0:3], v[220:223], v[122:125], v[74:77]
	s_waitcnt lgkmcnt(0)
	v_mfma_f32_16x16x32_bf16 v[4:7], v[224:227], v[148:151], v[0:3]
	v_mfma_f32_16x16x32_bf16 v[0:3], v[220:223], v[212:215], v[78:81]
	v_mfma_f32_16x16x32_bf16 v[0:3], v[224:227], v[216:219], v[0:3]
	s_setprio 0
	s_barrier
	v_add_u32_e32 v48, s68, v127
	v_add_u32_e32 v137, v48, v126
	s_mov_b32 m0, s14
	ds_read_b128 v[228:231], v137
	ds_read_b128 v[232:235], v137 offset:1024
	ds_read_b128 v[236:239], v137 offset:2048
	ds_read_b128 v[240:243], v137 offset:3072
	buffer_load_dwordx4 v133, s[4:7], s35 offen lds
	s_mov_b32 m0, s15
	s_nop 0
	buffer_load_dwordx4 v133, s[4:7], s36 offen lds
	s_barrier
	s_waitcnt lgkmcnt(0)
	s_setprio 1
	s_waitcnt lgkmcnt(3)
	v_mfma_f32_16x16x32_bf16 v[48:51], v[40:43], v[228:231], v[98:101]
	s_waitcnt lgkmcnt(1)
	v_mfma_f32_16x16x32_bf16 v[40:43], v[40:43], v[236:239], v[102:105]
	s_waitcnt lgkmcnt(0)
	v_mfma_f32_16x16x32_bf16 v[56:59], v[44:47], v[240:243], v[40:43]
	v_mfma_f32_16x16x32_bf16 v[40:43], v[82:85], v[228:231], v[106:109]
	v_mfma_f32_16x16x32_bf16 v[52:55], v[86:89], v[232:235], v[40:43]
	v_mfma_f32_16x16x32_bf16 v[40:43], v[82:85], v[236:239], v[110:113]
	v_mfma_f32_16x16x32_bf16 v[60:63], v[44:47], v[232:235], v[48:51]
	v_mfma_f32_16x16x32_bf16 v[48:51], v[86:89], v[240:243], v[40:43]
	v_mfma_f32_16x16x32_bf16 v[40:43], v[90:93], v[228:231], v[114:117]
	v_mfma_f32_16x16x32_bf16 v[32:35], v[90:93], v[236:239], v[32:35]
	v_mfma_f32_16x16x32_bf16 v[44:47], v[94:97], v[232:235], v[40:43]
	v_mfma_f32_16x16x32_bf16 v[40:43], v[94:97], v[240:243], v[32:35]
	v_mfma_f32_16x16x32_bf16 v[32:35], v[220:223], v[228:231], v[36:39]
	v_mfma_f32_16x16x32_bf16 v[36:39], v[224:227], v[232:235], v[32:35]
	v_mfma_f32_16x16x32_bf16 v[32:35], v[220:223], v[236:239], v[118:121]
	v_mfma_f32_16x16x32_bf16 v[32:35], v[224:227], v[240:243], v[32:35]
	s_setprio 0
	s_mov_b32 m0, s47
	s_barrier
	ds_read_b128 v[96:99], v129 offset:49152
	ds_read_b128 v[100:103], v129 offset:50176
	ds_read_b128 v[104:107], v130 offset:49152
	ds_read_b128 v[108:111], v130 offset:50176
	ds_read_b128 v[220:223], v131 offset:49152
	ds_read_b128 v[224:227], v131 offset:50176
	ds_read_b128 v[244:247], v132 offset:49152
	ds_read_b128 v[248:251], v132 offset:50176
	buffer_load_dwordx4 v133, s[56:59], s35 offen lds
	s_mov_b32 m0, s67
	s_nop 0
	buffer_load_dwordx4 v133, s[56:59], s36 offen lds
	s_barrier
	s_waitcnt lgkmcnt(0)
	s_setprio 1
	s_waitcnt lgkmcnt(7)
	v_mfma_f32_16x16x32_bf16 v[64:67], v[96:99], v[122:125], v[152:155]
	s_waitcnt lgkmcnt(6)
	v_mfma_f32_16x16x32_bf16 v[92:95], v[100:103], v[148:151], v[64:67]
	v_mfma_f32_16x16x32_bf16 v[64:67], v[96:99], v[212:215], v[156:159]
	v_mfma_f32_16x16x32_bf16 v[88:91], v[100:103], v[216:219], v[64:67]
	s_waitcnt lgkmcnt(5)
	v_mfma_f32_16x16x32_bf16 v[64:67], v[104:107], v[122:125], v[160:163]
	s_waitcnt lgkmcnt(4)
	v_mfma_f32_16x16x32_bf16 v[84:87], v[108:111], v[148:151], v[64:67]
	v_mfma_f32_16x16x32_bf16 v[64:67], v[104:107], v[212:215], v[164:167]
	v_mfma_f32_16x16x32_bf16 v[80:83], v[108:111], v[216:219], v[64:67]
	s_waitcnt lgkmcnt(3)
	v_mfma_f32_16x16x32_bf16 v[64:67], v[220:223], v[122:125], v[168:171]
	s_waitcnt lgkmcnt(2)
	v_mfma_f32_16x16x32_bf16 v[76:79], v[224:227], v[148:151], v[64:67]
	v_mfma_f32_16x16x32_bf16 v[64:67], v[220:223], v[212:215], v[172:175]
	v_mfma_f32_16x16x32_bf16 v[72:75], v[224:227], v[216:219], v[64:67]
	s_waitcnt lgkmcnt(1)
	v_mfma_f32_16x16x32_bf16 v[64:67], v[244:247], v[122:125], v[176:179]
	s_waitcnt lgkmcnt(0)
	v_mfma_f32_16x16x32_bf16 v[68:71], v[248:251], v[148:151], v[64:67]
	v_mfma_f32_16x16x32_bf16 v[64:67], v[244:247], v[212:215], v[180:183]
	v_mfma_f32_16x16x32_bf16 v[64:67], v[248:251], v[216:219], v[64:67]
	s_setprio 0
	s_barrier
	s_mov_b32 s84, 0x40180
	s_mov_b32 m0, s78
	s_nop 0
	buffer_load_dwordx4 v133, s[4:7], s84 offen lds
	s_mov_b32 m0, s79
	s_nop 0
	buffer_load_dwordx4 v133, s[4:7], s37 offen lds
	s_waitcnt vmcnt(6)
	s_barrier
	s_setprio 1
	v_mfma_f32_16x16x32_bf16 v[112:115], v[96:99], v[228:231], v[184:187]
	v_mfma_f32_16x16x32_bf16 v[96:99], v[96:99], v[236:239], v[188:191]
	v_mfma_f32_16x16x32_bf16 v[120:123], v[100:103], v[240:243], v[96:99]
	v_mfma_f32_16x16x32_bf16 v[96:99], v[104:107], v[228:231], v[192:195]
	v_mfma_f32_16x16x32_bf16 v[116:119], v[108:111], v[232:235], v[96:99]
	v_mfma_f32_16x16x32_bf16 v[96:99], v[104:107], v[236:239], v[196:199]
	v_mfma_f32_16x16x32_bf16 v[124:127], v[100:103], v[232:235], v[112:115]
	v_mfma_f32_16x16x32_bf16 v[112:115], v[108:111], v[240:243], v[96:99]
	v_mfma_f32_16x16x32_bf16 v[96:99], v[220:223], v[228:231], v[200:203]
	v_mfma_f32_16x16x32_bf16 v[108:111], v[224:227], v[232:235], v[96:99]
	v_mfma_f32_16x16x32_bf16 v[96:99], v[220:223], v[236:239], v[204:207]
	v_mfma_f32_16x16x32_bf16 v[104:107], v[224:227], v[240:243], v[96:99]
	v_mfma_f32_16x16x32_bf16 v[96:99], v[244:247], v[228:231], v[208:211]
	v_mfma_f32_16x16x32_bf16 v[100:103], v[248:251], v[232:235], v[96:99]
	v_mfma_f32_16x16x32_bf16 v[96:99], v[244:247], v[236:239], v[144:147]
	v_mfma_f32_16x16x32_bf16 v[96:99], v[248:251], v[240:243], v[96:99]
	s_setprio 0
	s_mov_b32 s84, 0
	s_mov_b32 s85, 0x60280
	s_barrier

; #define WAIT_V(n) asm volatile("s_waitcnt vmcnt(" #n ")" ::: "memory")
; #define BAR __builtin_amdgcn_s_barrier()
; template <bool PEEL = false>
; __device__ __forceinline__ void gemm_tile(f32x4 (&acc)[2][2][4][2], const u16* __restrict__ A, int lda,
;                                           const u16* __restrict__ B, int K) {
;     ...
;   STAGE_B(SB(0, 0), 0, 0); STAGE_A(SA(0, 0), 0, 0);
;   STAGE_B(SB(0, 1), 1, 0); STAGE_A(SA(0, 1), 1, 0);
;   if (wr == 1) BAR;
;   WAIT_V(4); BAR;
;   STAGE_B(SB(1, 0), 0, 1); STAGE_A(SA(1, 0), 0, 1); STAGE_B(SB(1, 1), 1, 1);
; __device__ __forceinline__ void gemm_inproj(const u16* __restrict__ A, const u16* __restrict__ Wt, u16* __restrict__ proj,
;                             u16* __restrict__ kb  , u16* __restrict__ vt  ) {
;     ...
;     if (nt == 5) {
; #pragma unroll
;       for (int ai = 0; ai < 2; ++ai)
; #pragma unroll
;         for (int m = 0; m < 4; ++m) {
;           const int row = ai * 128 + wr * 64 + m * 16 + fq * 4;
;           const float r0 = rstd[row], r1 = rstd[row + 1], r2 = rstd[row + 2], r3 = rstd[row + 3];
; #pragma unroll
;           for (int bj = 0; bj < 2; ++bj)
; #pragma unroll
;             for (int n = 0; n < 2; ++n) {
;               const int c = wc * 64 + fr * 4 + bj * 2 + n;
;               uint2 v;
;               v.x = pack2(acc[ai][bj][m][n][0] * r0, acc[ai][bj][m][n][1] * r1);
;               v.y = pack2(acc[ai][bj][m][n][2] * r2, acc[ai][bj][m][n][3] * r3);
;               __builtin_nontemporal_store(u32x2{v.x, v.y}, (u32x2*)(vt + (size_t)c * SEQ + row));
;             }
.LBB0_268:
	s_or_b64 exec, exec, s[4:5]
	s_cmp_eq_u32 s21, 15
	s_cbranch_scc1 .Lpf3_skip
	v_and_b32_e32 v200, 63, v254
	v_lshlrev_b32_e32 v201, 4, v200
	v_and_b32_e32 v202, 32, v200
	v_xor_b32_e32 v201, v201, v202
	v_lshrrev_b32_e32 v203, 6, v201
	v_and_b32_e32 v201, 63, v201
	v_lshl_add_u32 v201, v203, 11, v201
	v_lshrrev_b32_e32 v203, 6, v254
	v_and_b32_e32 v204, 1, v203
	v_lshl_add_u32 v201, v204, 6, v201
	v_lshrrev_b32_e32 v203, 1, v203
	v_lshl_add_u32 v200, v203, 15, v201
	s_add_i32 s14, s21, 1
	s_lshl_b32 s14, s14, 19
	s_add_u32 s4, s1, s14
	s_addc_u32 s5, s20, 0
	s_and_b32 s5, s5, 0xffff
	s_mov_b32 m0, s17
	s_nop 0
	buffer_load_dwordx4 v200, s[4:7], 0 offen lds
	s_mov_b32 m0, s40
	s_nop 0
	buffer_load_dwordx4 v200, s[4:7], s7 offen lds
	s_mov_b32 m0, s16
	s_nop 0
	buffer_load_dwordx4 v200, s[56:59], 0 offen lds
	s_mov_b32 m0, s41
	s_nop 0
	buffer_load_dwordx4 v200, s[56:59], s7 offen lds
	s_mov_b32 m0, s42
	s_nop 0
	buffer_load_dwordx4 v200, s[4:7], s22 offen lds
	s_mov_b32 m0, s43
	s_nop 0
	buffer_load_dwordx4 v200, s[4:7], s23 offen lds
	s_mov_b32 m0, s45
	s_nop 0
	buffer_load_dwordx4 v200, s[56:59], s22 offen lds
	s_mov_b32 m0, s46
	s_nop 0
	buffer_load_dwordx4 v200, s[56:59], s23 offen lds
	s_add_i32 m0, s16, 0x18000
	s_nop 0
	buffer_load_dwordx4 v200, s[4:7], s24 offen lds
	s_add_i32 m0, s16, 0x1a000
	s_nop 0
	buffer_load_dwordx4 v200, s[4:7], s25 offen lds
	s_mov_b32 m0, s47
	s_nop 0
	buffer_load_dwordx4 v200, s[56:59], s24 offen lds
	s_mov_b32 m0, s67
	s_nop 0
	buffer_load_dwordx4 v200, s[56:59], s25 offen lds
	s_mov_b32 m0, s78
	s_nop 0
	buffer_load_dwordx4 v200, s[4:7], s26 offen lds
	s_mov_b32 m0, s79
	s_nop 0
	buffer_load_dwordx4 v200, s[4:7], s27 offen lds
.Lpf3_skip:
	v_mov_b32_e32 v144, v139
	v_mov_b32_e32 v145, v141
	v_mov_b32_e32 v146, v138
	v_mov_b32_e32 v143, v140
	s_mov_b64 s[4:5], -1
	s_mov_b64 s[14:15], 0
	s_cmp_lt_i32 s21, 5
	s_mov_b64 s[16:17], 0
	s_cbranch_scc1 .LBB0_274
	s_cmp_eq_u32 s21, 5
	s_mov_b64 s[16:17], -1
	s_cbranch_scc0 .LBB0_271
	v_lshlrev_b32_e32 v128, 6, v146
	v_lshl_add_u32 v128, v145, 2, v128
	v_lshl_add_u32 v130, v128, 2, 0
	v_add_u32_e32 v147, 0x24000, v130
	ds_read_b128 v[148:151], v147
	ds_read_b128 v[152:155], v147 offset:64
	v_lshlrev_b32_e32 v129, 2, v143
	v_lshl_add_u32 v136, v144, 6, v129
	v_ashrrev_i32_e32 v129, 31, v128
	s_waitcnt lgkmcnt(1)
	v_pk_mul_f32 v[130:131], v[112:113], v[148:149]
	v_ashrrev_i32_e32 v137, 31, v136
	v_cvt_pk_bf16_f32 v132, v130, v131
	v_pk_mul_f32 v[130:131], v[114:115], v[150:151]
	v_lshl_add_u64 v[156:157], v[128:129], 1, s[12:13]
	v_cvt_pk_bf16_f32 v133, v130, v131
	v_lshlrev_b64 v[130:131], 12, v[136:137]
	v_lshl_add_u64 v[134:135], v[156:157], 0, v[130:131]
	global_store_dwordx2 v[134:135], v[132:133], off nt
	v_mul_f32_e32 v129, v116, v148
	v_mul_f32_e32 v133, v117, v149
	v_or_b32_e32 v132, 1, v136
	v_cvt_pk_bf16_f32 v134, v129, v133
	v_mul_f32_e32 v129, v118, v150
	v_mul_f32_e32 v133, v119, v151
	v_cvt_pk_bf16_f32 v135, v129, v133
	v_ashrrev_i32_e32 v133, 31, v132
	v_lshlrev_b64 v[132:133], 12, v[132:133]
	v_lshl_add_u64 v[158:159], v[156:157], 0, v[132:133]
	global_store_dwordx2 v[158:159], v[134:135], off nt
	v_mul_f32_e32 v129, v120, v148
	v_mul_f32_e32 v135, v121, v149
	v_cvt_pk_bf16_f32 v158, v129, v135
	v_mul_f32_e32 v129, v122, v150
	v_mul_f32_e32 v135, v123, v151
	v_cvt_pk_bf16_f32 v159, v129, v135
	v_mul_f32_e32 v129, v124, v148
	v_mul_f32_e32 v137, v125, v149
	v_or_b32_e32 v134, 2, v136
	v_or_b32_e32 v136, 3, v136
	v_cvt_pk_bf16_f32 v148, v129, v137
	v_mul_f32_e32 v129, v126, v150
	v_mul_f32_e32 v137, v127, v151
	v_cvt_pk_bf16_f32 v149, v129, v137
	v_ashrrev_i32_e32 v137, 31, v136
	v_lshlrev_b64 v[136:137], 12, v[136:137]
	v_lshl_add_u64 v[150:151], v[156:157], 0, v[136:137]
	v_ashrrev_i32_e32 v135, 31, v134
	global_store_dwordx2 v[150:151], v[148:149], off nt
	v_add_u32_e32 v148, 16, v128
	v_lshlrev_b64 v[134:135], 12, v[134:135]
	v_ashrrev_i32_e32 v149, 31, v148
	v_lshl_add_u64 v[160:161], v[156:157], 0, v[134:135]
	v_lshl_add_u64 v[148:149], v[148:149], 1, s[12:13]
	s_waitcnt lgkmcnt(0)
	v_pk_mul_f32 v[150:151], v[96:97], v[152:153]
	v_pk_mul_f32 v[156:157], v[98:99], v[154:155]
	v_cvt_pk_bf16_f32 v150, v150, v151
	v_cvt_pk_bf16_f32 v151, v156, v157
	v_lshl_add_u64 v[156:157], v[148:149], 0, v[130:131]
	global_store_dwordx2 v[160:161], v[158:159], off nt
	global_store_dwordx2 v[156:157], v[150:151], off nt
	v_mul_f32_e32 v129, v100, v152
	v_mul_f32_e32 v150, v101, v153
	v_cvt_pk_bf16_f32 v150, v129, v150
	v_mul_f32_e32 v129, v102, v154
	v_mul_f32_e32 v151, v103, v155
	v_cvt_pk_bf16_f32 v151, v129, v151
	v_lshl_add_u64 v[156:157], v[148:149], 0, v[132:133]
	global_store_dwordx2 v[156:157], v[150:151], off nt
	v_mul_f32_e32 v129, v104, v152
	v_mul_f32_e32 v150, v105, v153
	v_cvt_pk_bf16_f32 v150, v129, v150
	v_mul_f32_e32 v129, v106, v154
	v_mul_f32_e32 v151, v107, v155
	v_cvt_pk_bf16_f32 v151, v129, v151
	v_lshl_add_u64 v[156:157], v[148:149], 0, v[134:135]
	global_store_dwordx2 v[156:157], v[150:151], off nt
	v_mul_f32_e32 v129, v108, v152
	v_mul_f32_e32 v150, v109, v153
	v_cvt_pk_bf16_f32 v150, v129, v150
	v_mul_f32_e32 v129, v110, v154
	v_mul_f32_e32 v151, v111, v155
	v_cvt_pk_bf16_f32 v151, v129, v151
	v_lshl_add_u64 v[148:149], v[148:149], 0, v[136:137]
	global_store_dwordx2 v[148:149], v[150:151], off nt
	ds_read_b128 v[148:151], v147 offset:128
	v_add_u32_e32 v152, 32, v128
	v_ashrrev_i32_e32 v153, 31, v152
	v_lshl_add_u64 v[156:157], v[152:153], 1, s[12:13]
	ds_read_b128 v[152:155], v147 offset:192
	s_waitcnt lgkmcnt(1)
; __device__ __forceinline__ void gemm_inproj(const u16* __restrict__ A, const u16* __restrict__ Wt, u16* __restrict__ proj,
;                             u16* __restrict__ kb  , u16* __restrict__ vt  ) {
;     ...
;     if (nt == 5) {
; #pragma unroll
;       for (int ai = 0; ai < 2; ++ai)
; #pragma unroll
;         for (int m = 0; m < 4; ++m) {
;           const int row = ai * 128 + wr * 64 + m * 16 + fq * 4;
;           const float r0 = rstd[row], r1 = rstd[row + 1], r2 = rstd[row + 2], r3 = rstd[row + 3];
; #pragma unroll
;           for (int bj = 0; bj < 2; ++bj)
; #pragma unroll
;             for (int n = 0; n < 2; ++n) {
;               const int c = wc * 64 + fr * 4 + bj * 2 + n;
;               uint2 v;
;               v.x = pack2(acc[ai][bj][m][n][0] * r0, acc[ai][bj][m][n][1] * r1);
;               v.y = pack2(acc[ai][bj][m][n][2] * r2, acc[ai][bj][m][n][3] * r3);
;               __builtin_nontemporal_store(u32x2{v.x, v.y}, (u32x2*)(vt + (size_t)c * SEQ + row));
;             }
	v_pk_mul_f32 v[158:159], v[80:81], v[148:149]
	v_pk_mul_f32 v[160:161], v[82:83], v[150:151]
	v_cvt_pk_bf16_f32 v158, v158, v159
	v_cvt_pk_bf16_f32 v159, v160, v161
	v_lshl_add_u64 v[160:161], v[156:157], 0, v[130:131]
	global_store_dwordx2 v[160:161], v[158:159], off nt
	v_mul_f32_e32 v129, v84, v148
	v_mul_f32_e32 v158, v85, v149
	v_cvt_pk_bf16_f32 v158, v129, v158
	v_mul_f32_e32 v129, v86, v150
	v_mul_f32_e32 v159, v87, v151
	v_cvt_pk_bf16_f32 v159, v129, v159
	v_lshl_add_u64 v[160:161], v[156:157], 0, v[132:133]
	global_store_dwordx2 v[160:161], v[158:159], off nt
	v_mul_f32_e32 v129, v88, v148
	v_mul_f32_e32 v158, v89, v149
	v_cvt_pk_bf16_f32 v158, v129, v158
	v_mul_f32_e32 v129, v90, v150
	v_mul_f32_e32 v159, v91, v151
	v_cvt_pk_bf16_f32 v159, v129, v159
	v_mul_f32_e32 v129, v92, v148
	v_mul_f32_e32 v148, v93, v149
	v_cvt_pk_bf16_f32 v148, v129, v148
	v_mul_f32_e32 v129, v94, v150
	v_mul_f32_e32 v149, v95, v151
	v_cvt_pk_bf16_f32 v149, v129, v149
	v_lshl_add_u64 v[150:151], v[156:157], 0, v[136:137]
	global_store_dwordx2 v[150:151], v[148:149], off nt
	v_add_u32_e32 v148, 48, v128
	v_ashrrev_i32_e32 v149, 31, v148
	v_lshl_add_u64 v[160:161], v[156:157], 0, v[134:135]
	v_lshl_add_u64 v[148:149], v[148:149], 1, s[12:13]
	s_waitcnt lgkmcnt(0)
	v_pk_mul_f32 v[150:151], v[64:65], v[152:153]
	v_pk_mul_f32 v[156:157], v[66:67], v[154:155]
	v_cvt_pk_bf16_f32 v150, v150, v151
	v_cvt_pk_bf16_f32 v151, v156, v157
	v_lshl_add_u64 v[156:157], v[148:149], 0, v[130:131]
	global_store_dwordx2 v[160:161], v[158:159], off nt
	global_store_dwordx2 v[156:157], v[150:151], off nt
	v_mul_f32_e32 v129, v68, v152
	v_mul_f32_e32 v150, v69, v153
	v_cvt_pk_bf16_f32 v150, v129, v150
	v_mul_f32_e32 v129, v70, v154
	v_mul_f32_e32 v151, v71, v155
	v_cvt_pk_bf16_f32 v151, v129, v151
	v_lshl_add_u64 v[156:157], v[148:149], 0, v[132:133]
	global_store_dwordx2 v[156:157], v[150:151], off nt
	v_mul_f32_e32 v129, v72, v152
	v_mul_f32_e32 v150, v73, v153
	v_cvt_pk_bf16_f32 v150, v129, v150
	v_mul_f32_e32 v129, v74, v154
	v_mul_f32_e32 v151, v75, v155
	v_cvt_pk_bf16_f32 v151, v129, v151
	v_lshl_add_u64 v[156:157], v[148:149], 0, v[134:135]
	global_store_dwordx2 v[156:157], v[150:151], off nt
	v_mul_f32_e32 v129, v76, v152
	v_mul_f32_e32 v150, v77, v153
	v_cvt_pk_bf16_f32 v150, v129, v150
	v_mul_f32_e32 v129, v78, v154
	v_mul_f32_e32 v151, v79, v155
	v_cvt_pk_bf16_f32 v151, v129, v151
	v_lshl_add_u64 v[148:149], v[148:149], 0, v[136:137]
	global_store_dwordx2 v[148:149], v[150:151], off nt
	ds_read_b128 v[148:151], v147 offset:512
	v_add_u32_e32 v152, 0x80, v128
	v_ashrrev_i32_e32 v153, 31, v152
	v_lshl_add_u64 v[156:157], v[152:153], 1, s[12:13]
	ds_read_b128 v[152:155], v147 offset:576
	s_waitcnt lgkmcnt(1)
	v_pk_mul_f32 v[158:159], v[48:49], v[148:149]
	v_pk_mul_f32 v[160:161], v[50:51], v[150:151]
	v_cvt_pk_bf16_f32 v158, v158, v159
	v_cvt_pk_bf16_f32 v159, v160, v161
	v_lshl_add_u64 v[160:161], v[156:157], 0, v[130:131]
	global_store_dwordx2 v[160:161], v[158:159], off nt
	v_mul_f32_e32 v129, v52, v148
	v_mul_f32_e32 v158, v53, v149
	v_cvt_pk_bf16_f32 v158, v129, v158
	v_mul_f32_e32 v129, v54, v150
	v_mul_f32_e32 v159, v55, v151
	v_cvt_pk_bf16_f32 v159, v129, v159
	v_lshl_add_u64 v[160:161], v[156:157], 0, v[132:133]
	global_store_dwordx2 v[160:161], v[158:159], off nt
	v_mul_f32_e32 v129, v56, v148
	v_mul_f32_e32 v158, v57, v149
	v_cvt_pk_bf16_f32 v158, v129, v158
	v_mul_f32_e32 v129, v58, v150
	v_mul_f32_e32 v159, v59, v151
	v_cvt_pk_bf16_f32 v159, v129, v159
	v_mul_f32_e32 v129, v60, v148
	v_mul_f32_e32 v148, v61, v149
	v_cvt_pk_bf16_f32 v148, v129, v148
	v_mul_f32_e32 v129, v62, v150
	v_mul_f32_e32 v149, v63, v151
	v_cvt_pk_bf16_f32 v149, v129, v149
	v_lshl_add_u64 v[150:151], v[156:157], 0, v[136:137]
	global_store_dwordx2 v[150:151], v[148:149], off nt
	v_add_u32_e32 v148, 0x90, v128
	v_ashrrev_i32_e32 v149, 31, v148
	v_lshl_add_u64 v[160:161], v[156:157], 0, v[134:135]
	v_lshl_add_u64 v[148:149], v[148:149], 1, s[12:13]
	s_waitcnt lgkmcnt(0)
; __device__ __forceinline__ void gemm_inproj(const u16* __restrict__ A, const u16* __restrict__ Wt, u16* __restrict__ proj,
;                             u16* __restrict__ kb  , u16* __restrict__ vt  ) {
;     ...
;     if (nt == 5) {
; #pragma unroll
;       for (int ai = 0; ai < 2; ++ai)
; #pragma unroll
;         for (int m = 0; m < 4; ++m) {
;           const int row = ai * 128 + wr * 64 + m * 16 + fq * 4;
;           const float r0 = rstd[row], r1 = rstd[row + 1], r2 = rstd[row + 2], r3 = rstd[row + 3];
; #pragma unroll
;           for (int bj = 0; bj < 2; ++bj)
; #pragma unroll
;             for (int n = 0; n < 2; ++n) {
;               const int c = wc * 64 + fr * 4 + bj * 2 + n;
;               uint2 v;
;               v.x = pack2(acc[ai][bj][m][n][0] * r0, acc[ai][bj][m][n][1] * r1);
;               v.y = pack2(acc[ai][bj][m][n][2] * r2, acc[ai][bj][m][n][3] * r3);
;               __builtin_nontemporal_store(u32x2{v.x, v.y}, (u32x2*)(vt + (size_t)c * SEQ + row));
;             }
	v_pk_mul_f32 v[150:151], v[32:33], v[152:153]
	v_pk_mul_f32 v[156:157], v[34:35], v[154:155]
	v_cvt_pk_bf16_f32 v150, v150, v151
	v_cvt_pk_bf16_f32 v151, v156, v157
	v_lshl_add_u64 v[156:157], v[148:149], 0, v[130:131]
	global_store_dwordx2 v[160:161], v[158:159], off nt
	global_store_dwordx2 v[156:157], v[150:151], off nt
	v_mul_f32_e32 v129, v36, v152
	v_mul_f32_e32 v150, v37, v153
	v_cvt_pk_bf16_f32 v150, v129, v150
	v_mul_f32_e32 v129, v38, v154
	v_mul_f32_e32 v151, v39, v155
	v_cvt_pk_bf16_f32 v151, v129, v151
	v_lshl_add_u64 v[156:157], v[148:149], 0, v[132:133]
	global_store_dwordx2 v[156:157], v[150:151], off nt
	v_mul_f32_e32 v129, v40, v152
	v_mul_f32_e32 v150, v41, v153
	v_cvt_pk_bf16_f32 v150, v129, v150
	v_mul_f32_e32 v129, v42, v154
	v_mul_f32_e32 v151, v43, v155
	v_cvt_pk_bf16_f32 v151, v129, v151
	v_lshl_add_u64 v[156:157], v[148:149], 0, v[134:135]
	global_store_dwordx2 v[156:157], v[150:151], off nt
	v_mul_f32_e32 v129, v44, v152
	v_mul_f32_e32 v150, v45, v153
	v_cvt_pk_bf16_f32 v150, v129, v150
	v_mul_f32_e32 v129, v46, v154
	v_mul_f32_e32 v151, v47, v155
	v_cvt_pk_bf16_f32 v151, v129, v151
	v_lshl_add_u64 v[148:149], v[148:149], 0, v[136:137]
	global_store_dwordx2 v[148:149], v[150:151], off nt
	ds_read_b128 v[148:151], v147 offset:640
	v_add_u32_e32 v152, 0xa0, v128
	v_ashrrev_i32_e32 v153, 31, v152
	v_lshl_add_u64 v[156:157], v[152:153], 1, s[12:13]
	ds_read_b128 v[152:155], v147 offset:704
	s_waitcnt lgkmcnt(1)
	v_pk_mul_f32 v[158:159], v[16:17], v[148:149]
	v_pk_mul_f32 v[160:161], v[18:19], v[150:151]
	v_cvt_pk_bf16_f32 v158, v158, v159
	v_cvt_pk_bf16_f32 v159, v160, v161
	v_lshl_add_u64 v[160:161], v[156:157], 0, v[130:131]
	v_mul_f32_e32 v129, v20, v148
	v_mul_f32_e32 v147, v21, v149
	global_store_dwordx2 v[160:161], v[158:159], off nt
	v_cvt_pk_bf16_f32 v158, v129, v147
	v_mul_f32_e32 v129, v22, v150
	v_mul_f32_e32 v147, v23, v151
	v_cvt_pk_bf16_f32 v159, v129, v147
	v_lshl_add_u64 v[160:161], v[156:157], 0, v[132:133]
	v_mul_f32_e32 v129, v24, v148
	v_mul_f32_e32 v147, v25, v149
	global_store_dwordx2 v[160:161], v[158:159], off nt
	v_cvt_pk_bf16_f32 v158, v129, v147
	v_mul_f32_e32 v129, v26, v150
	v_mul_f32_e32 v147, v27, v151
	v_cvt_pk_bf16_f32 v159, v129, v147
	v_mul_f32_e32 v129, v28, v148
	v_mul_f32_e32 v147, v29, v149
	v_cvt_pk_bf16_f32 v148, v129, v147
	v_mul_f32_e32 v129, v30, v150
	v_mul_f32_e32 v147, v31, v151
	v_add_u32_e32 v128, 0xb0, v128
	v_cvt_pk_bf16_f32 v149, v129, v147
	v_lshl_add_u64 v[150:151], v[156:157], 0, v[136:137]
	v_ashrrev_i32_e32 v129, 31, v128
	global_store_dwordx2 v[150:151], v[148:149], off nt
	v_lshl_add_u64 v[128:129], v[128:129], 1, s[12:13]
	s_waitcnt lgkmcnt(0)
	v_pk_mul_f32 v[148:149], v[0:1], v[152:153]
	v_pk_mul_f32 v[150:151], v[2:3], v[154:155]
	v_lshl_add_u64 v[160:161], v[156:157], 0, v[134:135]
	v_cvt_pk_bf16_f32 v148, v148, v149
	v_cvt_pk_bf16_f32 v149, v150, v151
	v_lshl_add_u64 v[130:131], v[128:129], 0, v[130:131]
	global_store_dwordx2 v[160:161], v[158:159], off nt
	global_store_dwordx2 v[130:131], v[148:149], off nt
	v_mul_f32_e32 v130, v4, v152
	v_mul_f32_e32 v131, v5, v153
	v_cvt_pk_bf16_f32 v130, v130, v131
	v_mul_f32_e32 v131, v6, v154
	v_mul_f32_e32 v147, v7, v155
	v_cvt_pk_bf16_f32 v131, v131, v147
	v_lshl_add_u64 v[132:133], v[128:129], 0, v[132:133]
	global_store_dwordx2 v[132:133], v[130:131], off nt
	v_mul_f32_e32 v130, v8, v152
	v_mul_f32_e32 v131, v9, v153
	v_cvt_pk_bf16_f32 v130, v130, v131
	v_mul_f32_e32 v131, v10, v154
	v_mul_f32_e32 v132, v11, v155
	v_cvt_pk_bf16_f32 v131, v131, v132
	v_lshl_add_u64 v[132:133], v[128:129], 0, v[134:135]
	global_store_dwordx2 v[132:133], v[130:131], off nt
	v_mul_f32_e32 v130, v12, v152
	v_mul_f32_e32 v131, v13, v153
	v_cvt_pk_bf16_f32 v130, v130, v131
	v_mul_f32_e32 v131, v14, v154
	v_mul_f32_e32 v132, v15, v155
	v_cvt_pk_bf16_f32 v131, v131, v132
	v_lshl_add_u64 v[128:129], v[128:129], 0, v[136:137]
	global_store_dwordx2 v[128:129], v[130:131], off nt
	s_mov_b64 s[16:17], 0
